# differential attention: LDS-DMA pieces issued in the P.V gaps of the first key half instead of between stage D's bare MFMAs
# baseline (speedup 1.0000x reference)
.LBB0_319:
	s_add_i32 s6, s39, 0xfffe8000
	s_and_b32 s6, s6, 0x18000
	s_add_i32 s12, s6, 0
	s_add_i32 s6, s12, s40
	v_add_u32_e32 v76, s6, v164
	s_lshl_b32 s6, s3, 6
	v_cvt_f32_i32_e32 v80, s6
	v_add_u32_e32 v68, v76, v163
	v_add_u32_e32 v72, v76, v165
	v_add_u32_e32 v77, v76, v166
	v_add_u32_e32 v81, v76, v167
	ds_read_b128 v[64:67], v68
	ds_read_b128 v[114:117], v68 offset:4096
	ds_read_b128 v[68:71], v72
	ds_read_b128 v[124:127], v72 offset:4096
	ds_read_b128 v[72:75], v77
	ds_read_b128 v[134:137], v77 offset:4096
	ds_read_b128 v[76:79], v81
	ds_read_b128 v[120:123], v81 offset:4096
	s_cmp_lt_i32 s3, s24
	s_cselect_b64 s[6:7], -1, 0
	v_sub_f32_e32 v113, v170, v80
	v_cndmask_b32_e64 v118, -v156, v156, s[6:7]
	v_mul_f32_e32 v119, 0x41000000, v118
	v_fma_f32 v80, v118, -v113, -v155
	v_add_f32_e32 v84, v119, v80
	v_add_f32_e32 v81, v118, v80
	v_add_f32_e32 v88, v119, v84
	v_add_f32_e32 v82, v118, v81
	v_add_f32_e32 v85, v118, v84
	v_add_f32_e32 v92, v119, v88
	v_add_f32_e32 v83, v118, v82
	v_add_f32_e32 v86, v118, v85
	v_add_f32_e32 v89, v118, v88
	v_add_f32_e32 v87, v118, v86
	v_add_f32_e32 v90, v118, v89
	v_add_f32_e32 v93, v118, v92
	v_add_f32_e32 v91, v118, v90
	v_add_f32_e32 v94, v118, v93
	v_add_f32_e32 v95, v118, v94
	s_nop 1
	s_waitcnt lgkmcnt(7)
	v_mfma_f32_32x32x16_bf16 v[80:95], v[64:67], v[96:99], v[80:95]
	v_sub_f32_e32 v64, 0x42000000, v113
	v_fma_f32 v64, v118, v64, -v155
	v_add_f32_e32 v65, v118, v64
	v_add_u32_e32 v132, s12, v162
	v_add_f32_e32 v66, v118, v65
	v_add_f32_e32 v67, v118, v66
	s_waitcnt lgkmcnt(5)
	v_mfma_f32_32x32x16_bf16 v[80:95], v[68:71], v[100:103], v[80:95]
	v_add_f32_e32 v68, v119, v64
	v_add_f32_e32 v69, v118, v68
	v_add_f32_e32 v70, v118, v69
	v_add_f32_e32 v71, v118, v70
	s_waitcnt lgkmcnt(3)
	v_mfma_f32_32x32x16_bf16 v[80:95], v[72:75], v[104:107], v[80:95]
	v_add_f32_e32 v72, v119, v68
	v_add_f32_e32 v73, v118, v72
	v_add_f32_e32 v74, v118, v73
	v_add_f32_e32 v75, v118, v74
	s_waitcnt lgkmcnt(1)
	v_mfma_f32_32x32x16_bf16 v[80:95], v[76:79], v[108:111], v[80:95]
	v_add_f32_e32 v76, v119, v72
	v_add_f32_e32 v77, v118, v76
	v_add_f32_e32 v78, v118, v77
	v_add_f32_e32 v79, v118, v78
	s_nop 1
	s_nop 7
	v_exp_f32_e32 v80, v80
	ds_read_b64_tr_b16 v[138:139], v132 offset:16384
	ds_read_b64_tr_b16 v[140:141], v132 offset:16896
	ds_read_b64_tr_b16 v[142:143], v132 offset:17408
	ds_read_b64_tr_b16 v[144:145], v132 offset:17920
	v_exp_f32_e32 v81, v81
	v_exp_f32_e32 v82, v82
	v_exp_f32_e32 v83, v83
	v_add_f32_e32 v112, v112, v80
	v_add_f32_e32 v112, v81, v112
	v_add_f32_e32 v112, v82, v112
	v_add_f32_e32 v112, v83, v112
	v_mfma_f32_32x32x16_bf16 v[64:79], v[114:117], v[96:99], v[64:79]
	ds_read_b64_tr_b16 v[158:159], v132 offset:20480
	ds_read_b64_tr_b16 v[160:161], v132 offset:20992
	ds_read_b64_tr_b16 v[172:173], v132 offset:21504
	ds_read_b64_tr_b16 v[174:175], v132 offset:22016
	v_exp_f32_e32 v133, v84
	v_exp_f32_e32 v146, v85
	v_exp_f32_e32 v147, v86
	v_exp_f32_e32 v171, v87
	v_add_f32_e32 v84, v133, v112
	v_add_f32_e32 v84, v146, v84
	v_add_f32_e32 v84, v147, v84
	v_add_f32_e32 v84, v171, v84
	v_mfma_f32_32x32x16_bf16 v[64:79], v[124:127], v[100:103], v[64:79]
	ds_read_b64_tr_b16 v[124:125], v132 offset:24576
	ds_read_b64_tr_b16 v[126:127], v132 offset:25088
	ds_read_b64_tr_b16 v[116:117], v132 offset:25600
	ds_read_b64_tr_b16 v[118:119], v132 offset:26112
	v_exp_f32_e32 v88, v88
	v_exp_f32_e32 v89, v89
	v_exp_f32_e32 v90, v90
	v_exp_f32_e32 v91, v91
	v_add_f32_e32 v84, v88, v84
	v_add_f32_e32 v84, v89, v84
	v_add_f32_e32 v84, v90, v84
	v_add_f32_e32 v176, v91, v84
	v_mfma_f32_32x32x16_bf16 v[64:79], v[134:137], v[104:107], v[64:79]
	ds_read_b64_tr_b16 v[112:113], v132 offset:28672
	ds_read_b64_tr_b16 v[114:115], v132 offset:29184
	ds_read_b64_tr_b16 v[84:85], v132 offset:29696
	ds_read_b64_tr_b16 v[86:87], v132 offset:30208
	v_exp_f32_e32 v134, v92
	v_exp_f32_e32 v135, v93
	v_exp_f32_e32 v136, v94
	v_exp_f32_e32 v95, v95
	v_add_f32_e32 v92, v134, v176
	v_add_f32_e32 v92, v135, v92
	v_add_f32_e32 v92, v136, v92
	v_add_f32_e32 v137, v95, v92
	s_waitcnt lgkmcnt(14)
	v_mfma_f32_32x32x16_bf16 v[64:79], v[120:123], v[108:111], v[64:79]
	v_cvt_pk_bf16_f32 v120, v80, v81
	v_cvt_pk_bf16_f32 v121, v82, v83
	v_cvt_pk_bf16_f32 v122, v133, v146
	v_cvt_pk_bf16_f32 v123, v147, v171
	v_cvt_pk_bf16_f32 v92, v88, v89
	v_cvt_pk_bf16_f32 v93, v90, v91
	v_cvt_pk_bf16_f32 v94, v134, v135
	v_cvt_pk_bf16_f32 v95, v136, v95
	s_bitcmp1_b32 s26, 0
	s_cbranch_scc1 .Lda_pvplain
	s_cmp_ge_i32 s26, s34
	s_cbranch_scc1 .Lda_pvplain
	s_add_i32 s100, s26, 2
	s_and_b32 s100, s100, 3
	s_lshl_b32 s100, s100, 15
	s_add_i32 s101, s100, s43
	v_mfma_f32_32x32x16_bf16 v[0:15], v[138:141], v[120:123], v[0:15]
	ds_read_b64_tr_b16 v[80:81], v132 offset:18432
	ds_read_b64_tr_b16 v[82:83], v132 offset:18944
	s_mov_b32 m0, s101
	s_addk_i32 s101, 0x2000
	global_load_lds_dwordx4 v[186:187], off
	s_nop 0
	v_exp_f32_e32 v133, v64
	v_exp_f32_e32 v138, v65
	v_add_f32_e32 v64, v137, v133
	v_add_f32_e32 v64, v138, v64
	s_waitcnt lgkmcnt(14)
	v_mfma_f32_32x32x16_bf16 v[0:15], v[142:145], v[92:95], v[0:15]
	ds_read_b64_tr_b16 v[88:89], v132 offset:19456
	ds_read_b64_tr_b16 v[90:91], v132 offset:19968
	s_mov_b32 m0, s101
	s_add_i32 s101, s100, s45
	global_load_lds_dwordx4 v[188:189], off
	v_exp_f32_e32 v139, v66
	v_exp_f32_e32 v140, v67
	v_add_f32_e32 v64, v139, v64
	v_add_f32_e32 v134, v140, v64
	s_waitcnt lgkmcnt(14)
	v_mfma_f32_32x32x16_bf16 v[16:31], v[158:161], v[120:123], v[16:31]
	ds_read_b64_tr_b16 v[64:65], v132 offset:22528
	ds_read_b64_tr_b16 v[66:67], v132 offset:23040
	s_mov_b32 m0, s101
	s_add_i32 s101, s100, s46
	global_load_lds_dwordx4 v[190:191], off
	v_exp_f32_e32 v141, v68
	v_exp_f32_e32 v142, v69
	v_add_f32_e32 v68, v141, v134
	v_add_f32_e32 v68, v142, v68
	s_waitcnt lgkmcnt(14)
	v_mfma_f32_32x32x16_bf16 v[16:31], v[172:175], v[92:95], v[16:31]
	ds_read_b64_tr_b16 v[134:135], v132 offset:23552
	ds_read_b64_tr_b16 v[136:137], v132 offset:24064
	s_mov_b32 m0, s101
	s_add_i32 s100, s100, 0x8000
	global_load_lds_dwordx4 v[192:193], off
	s_add_i32 s101, s100, s43
	v_exp_f32_e32 v143, v70
	v_exp_f32_e32 v144, v71
	v_add_f32_e32 v68, v143, v68
	v_add_f32_e32 v145, v144, v68
	s_waitcnt lgkmcnt(14)
	v_mfma_f32_32x32x16_bf16 v[32:47], v[124:127], v[120:123], v[32:47]
	ds_read_b64_tr_b16 v[68:69], v132 offset:26624
	ds_read_b64_tr_b16 v[70:71], v132 offset:27136
	s_mov_b32 m0, s101
	s_addk_i32 s101, 0x2000
	global_load_lds_dwordx4 v[194:195], off
	v_exp_f32_e32 v124, v72
	v_exp_f32_e32 v125, v73
	v_add_f32_e32 v72, v124, v145
	v_add_f32_e32 v72, v125, v72
	s_waitcnt lgkmcnt(14)
	v_mfma_f32_32x32x16_bf16 v[32:47], v[116:119], v[92:95], v[32:47]
	ds_read_b64_tr_b16 v[116:117], v132 offset:27648
	ds_read_b64_tr_b16 v[118:119], v132 offset:28160
	s_mov_b32 m0, s101
	s_add_i32 s101, s100, s45
	global_load_lds_dwordx4 v[196:197], off
	v_exp_f32_e32 v126, v74
	v_exp_f32_e32 v127, v75
	v_add_f32_e32 v72, v126, v72
	v_add_f32_e32 v145, v127, v72
	s_waitcnt lgkmcnt(14)
	v_mfma_f32_32x32x16_bf16 v[48:63], v[112:115], v[120:123], v[48:63]
	ds_read_b64_tr_b16 v[72:73], v132 offset:30720
	ds_read_b64_tr_b16 v[74:75], v132 offset:31232
	s_mov_b32 m0, s101
	s_add_i32 s101, s100, s46
	global_load_lds_dwordx4 v[198:199], off
	v_exp_f32_e32 v113, v76
	v_exp_f32_e32 v114, v77
	v_add_f32_e32 v76, v113, v145
	v_add_f32_e32 v76, v114, v76
	s_waitcnt lgkmcnt(14)
	v_mfma_f32_32x32x16_bf16 v[48:63], v[84:87], v[92:95], v[48:63]
	v_exp_f32_e32 v95, v78
	ds_read_b64_tr_b16 v[84:85], v132 offset:31744
	ds_read_b64_tr_b16 v[86:87], v132 offset:32256
	s_mov_b32 m0, s101
	s_nop 0
	global_load_lds_dwordx4 v[200:201], off
	v_exp_f32_e32 v115, v79
	v_add_f32_e32 v76, v95, v76
	v_add_f32_e32 v112, v115, v76
	v_cvt_pk_bf16_f32 v76, v133, v138
	v_cvt_pk_bf16_f32 v77, v139, v140
	v_cvt_pk_bf16_f32 v78, v141, v142
	v_cvt_pk_bf16_f32 v79, v143, v144
	v_cvt_pk_bf16_f32 v92, v124, v125
	v_cvt_pk_bf16_f32 v93, v126, v127
	v_cvt_pk_bf16_f32 v94, v113, v114
	v_cvt_pk_bf16_f32 v95, v95, v115
	s_setprio 0
	s_branch .Lda_dplain
.Lda_pvplain:
	v_mfma_f32_32x32x16_bf16 v[0:15], v[138:141], v[120:123], v[0:15]
	ds_read_b64_tr_b16 v[80:81], v132 offset:18432
	ds_read_b64_tr_b16 v[82:83], v132 offset:18944
	s_nop 0
	v_exp_f32_e32 v133, v64
	v_exp_f32_e32 v138, v65
	v_add_f32_e32 v64, v137, v133
	v_add_f32_e32 v64, v138, v64
	s_waitcnt lgkmcnt(14)
	v_mfma_f32_32x32x16_bf16 v[0:15], v[142:145], v[92:95], v[0:15]
	ds_read_b64_tr_b16 v[88:89], v132 offset:19456
	ds_read_b64_tr_b16 v[90:91], v132 offset:19968
	v_exp_f32_e32 v139, v66
	v_exp_f32_e32 v140, v67
	v_add_f32_e32 v64, v139, v64
	v_add_f32_e32 v134, v140, v64
	s_waitcnt lgkmcnt(14)
	v_mfma_f32_32x32x16_bf16 v[16:31], v[158:161], v[120:123], v[16:31]
	ds_read_b64_tr_b16 v[64:65], v132 offset:22528
	ds_read_b64_tr_b16 v[66:67], v132 offset:23040
	v_exp_f32_e32 v141, v68
	v_exp_f32_e32 v142, v69
	v_add_f32_e32 v68, v141, v134
	v_add_f32_e32 v68, v142, v68
	s_waitcnt lgkmcnt(14)
	v_mfma_f32_32x32x16_bf16 v[16:31], v[172:175], v[92:95], v[16:31]
	ds_read_b64_tr_b16 v[134:135], v132 offset:23552
	ds_read_b64_tr_b16 v[136:137], v132 offset:24064
	v_exp_f32_e32 v143, v70
	v_exp_f32_e32 v144, v71
	v_add_f32_e32 v68, v143, v68
	v_add_f32_e32 v145, v144, v68
	s_waitcnt lgkmcnt(14)
	v_mfma_f32_32x32x16_bf16 v[32:47], v[124:127], v[120:123], v[32:47]
	ds_read_b64_tr_b16 v[68:69], v132 offset:26624
	ds_read_b64_tr_b16 v[70:71], v132 offset:27136
	v_exp_f32_e32 v124, v72
	v_exp_f32_e32 v125, v73
	v_add_f32_e32 v72, v124, v145
	v_add_f32_e32 v72, v125, v72
	s_waitcnt lgkmcnt(14)
	v_mfma_f32_32x32x16_bf16 v[32:47], v[116:119], v[92:95], v[32:47]
	ds_read_b64_tr_b16 v[116:117], v132 offset:27648
	ds_read_b64_tr_b16 v[118:119], v132 offset:28160
	v_exp_f32_e32 v126, v74
	v_exp_f32_e32 v127, v75
	v_add_f32_e32 v72, v126, v72
	v_add_f32_e32 v145, v127, v72
	s_waitcnt lgkmcnt(14)
	v_mfma_f32_32x32x16_bf16 v[48:63], v[112:115], v[120:123], v[48:63]
	ds_read_b64_tr_b16 v[72:73], v132 offset:30720
	ds_read_b64_tr_b16 v[74:75], v132 offset:31232
	v_exp_f32_e32 v113, v76
	v_exp_f32_e32 v114, v77
	v_add_f32_e32 v76, v113, v145
	v_add_f32_e32 v76, v114, v76
	s_waitcnt lgkmcnt(14)
	v_mfma_f32_32x32x16_bf16 v[48:63], v[84:87], v[92:95], v[48:63]
	v_exp_f32_e32 v95, v78
	ds_read_b64_tr_b16 v[84:85], v132 offset:31744
	ds_read_b64_tr_b16 v[86:87], v132 offset:32256
	v_exp_f32_e32 v115, v79
	v_add_f32_e32 v76, v95, v76
	v_add_f32_e32 v112, v115, v76
	v_cvt_pk_bf16_f32 v76, v133, v138
	v_cvt_pk_bf16_f32 v77, v139, v140
	v_cvt_pk_bf16_f32 v78, v141, v142
	v_cvt_pk_bf16_f32 v79, v143, v144
	v_cvt_pk_bf16_f32 v92, v124, v125
	v_cvt_pk_bf16_f32 v93, v126, v127
	v_cvt_pk_bf16_f32 v94, v113, v114
	v_cvt_pk_bf16_f32 v95, v95, v115
	s_setprio 0
